# plus: MIX2 (combine/gate/norm) row loop: the nine row loads hoisted to the top of each iteration (one memory round trip per row instead of six)
# speedup vs baseline: 1.0120x; 1.0016x over previous
; __device__ __forceinline__ f32x8 unpack8(u32x4 w) { f32x8 o; o[0] = bflo(w.x); o[1] = bfhi(w.x); o[2] = bflo(w.y); o[3] = bfhi(w.y); o[4] = bflo(w.z); o[5] = bfhi(w.z); o[6] = bflo(w.w); o[7] = bfhi(w.w); return o; }
; __device__ __forceinline__ u32x4 pack8(f32x8 v) { u32x4 w; w.x = pk2(v[0], v[1]); w.y = pk2(v[2], v[3]); w.z = pk2(v[4], v[5]); w.w = pk2(v[6], v[7]); return w; }
; __device__ __forceinline__ float siluf(float x) { return x * sigm(x); }
; __device__ __forceinline__ float gelu_tanh(float x) { const float y = 0.7978845608028654f * (x + 0.044715f * x * x * x); const float t = 1.0f - 2.0f * __builtin_amdgcn_rcpf(1.0f + __expf(2.0f * y)); return 0.5f * x * (1.0f + t); }
; __global__ void __launch_bounds__(512, 2) mega_fwd(Args args) {
;     ...
;                         for (int row = gw; row < THALF; row += NGW) {
;                             bf16* yr = YF + (size_t)row * YLD; const bf16* yb = YBK + (size_t)row * YLD; const bf16* pr = PROJ + (size_t)row * PLD;
;                             {
;                                 const f32x8 a = unpack8(*(const u32x4*)(yr + 8 * lane)), b = unpack8(*(const u32x4*)(yb + 8 * lane)), gt = unpack8(*(const u32x4*)(pr + PC_GATE + 8 * lane));
;                                 f32x8 o;
; #pragma unroll
;                                 for (int e = 0; e < 8; ++e) o[e] = (a[e] + b[e]) * gelu_tanh(gt[e]);
;                                 *(u32x4*)(yr + 8 * lane) = pack8(o);
;                             }
;                             {
;                                 const f32x8 a = unpack8(*(const u32x4*)(yr + 512 + 8 * lane)), b = unpack8(*(const u32x4*)(yb + 512 + 8 * lane)), z = unpack8(*(const u32x4*)(pr + PC_Z + 8 * lane));
;                                 f32x8 v; float ss = 0.f;
; #pragma unroll
;                                 for (int e = 0; e < 8; ++e) { v[e] = (a[e] + b[e]) * siluf(z[e]); ss += v[e] * v[e]; }
;                                 ss = wave_sum(ss);
;                                 const float rs = rsqrtf(ss * (1.0f / 512.0f) + EPSN);
;                                 *(u32x4*)(yr + 512 + 8 * lane) = pack8(v * rs * nw_s);
;                             }
;                             {
;                                 const f32x8 a = unpack8(*(const u32x4*)(yr + 1024 + 8 * lane)), b = unpack8(*(const u32x4*)(yb + 1024 + 8 * lane)), gg = unpack8(*(const u32x4*)(pr + PC_G + 8 * lane));
.LBB0_726:
	s_nop 0
	v_lshl_add_u64 v[26:27], s[4:5], 0, v[128:129]
	v_add_co_u32_e32 v24, vcc, 0x2c500000, v26
	s_mov_b32 s1, 0x15d00000
	s_nop 0
	v_addc_co_u32_e32 v25, vcc, 0, v27, vcc
	v_add_co_u32_e32 v28, vcc, 0x33d00000, v26
	global_load_dwordx4 v[30:33], v[24:25], off
	s_nop 0
	v_addc_co_u32_e32 v29, vcc, 0, v27, vcc
	v_lshl_add_u64 v[26:27], s[6:7], 0, v[128:129]
	v_add_co_u32_e32 v42, vcc, s1, v26
	global_load_dwordx4 v[34:37], v[28:29], off
	s_nop 0
	v_addc_co_u32_e32 v43, vcc, 0, v27, vcc
	global_load_dwordx4 v[38:41], v[42:43], off offset:1024
	v_add_co_u32_e32 v88, vcc, 0x15d01000, v26
	s_nop 1
	v_addc_co_u32_e32 v89, vcc, 0, v27, vcc
	global_load_dwordx4 v[64:67], v[24:25], off offset:1024
	global_load_dwordx4 v[68:71], v[28:29], off offset:1024
	global_load_dwordx4 v[72:75], v[42:43], off offset:2048
	global_load_dwordx4 v[76:79], v[24:25], off offset:2048
	global_load_dwordx4 v[80:83], v[28:29], off offset:2048
	global_load_dwordx4 v[84:87], v[88:89], off offset:3584
	s_mov_b32 s1, 0x15d01000
	s_add_i32 s0, s0, s58
	s_waitcnt vmcnt(0)
	v_lshlrev_b32_e32 v1, 16, v38
	v_and_b32_e32 v3, 0xffff0000, v38
	v_lshlrev_b32_e32 v5, 16, v39
	v_and_b32_e32 v7, 0xffff0000, v39
	v_lshlrev_b32_e32 v38, 16, v30
	v_lshlrev_b32_e32 v39, 16, v34
	v_and_b32_e32 v34, 0xffff0000, v34
	v_and_b32_e32 v30, 0xffff0000, v30
	v_add_f32_e32 v30, v34, v30
	v_mul_f32_e32 v34, 0x3d372713, v3
	v_mul_f32_e32 v34, v34, v3
	v_fma_f32 v34, v34, v3, v3
	v_mul_f32_e32 v34, 0x3f4c422a, v34
	v_add_f32_e32 v34, v34, v34
	v_mul_f32_e32 v34, 0x3fb8aa3b, v34
	v_exp_f32_e32 v34, v34
	v_mul_f32_e32 v3, 0.5, v3
	v_lshlrev_b32_e32 v17, 16, v40
	v_and_b32_e32 v19, 0xffff0000, v40
	v_add_f32_e32 v34, 1.0, v34
	v_rcp_f32_e32 v34, v34
	v_lshlrev_b32_e32 v21, 16, v41
	v_and_b32_e32 v23, 0xffff0000, v41
	v_add_f32_e32 v38, v39, v38
	v_fma_f32 v34, v34, -2.0, 1.0
	v_add_f32_e32 v34, 1.0, v34
	v_mul_f32_e32 v3, v3, v34
	v_mul_f32_e32 v3, v30, v3
	v_lshlrev_b32_e32 v30, 16, v31
	v_lshlrev_b32_e32 v34, 16, v35
	v_add_f32_e32 v30, v34, v30
	v_mul_f32_e32 v34, 0x3d372713, v5
	v_mul_f32_e32 v34, v34, v5
	v_fma_f32 v34, v34, v5, v5
	v_mul_f32_e32 v34, 0x3f4c422a, v34
	v_add_f32_e32 v34, v34, v34
	v_mul_f32_e32 v34, 0x3fb8aa3b, v34
	v_exp_f32_e32 v34, v34
	v_mul_f32_e32 v5, 0.5, v5
	v_and_b32_e32 v31, 0xffff0000, v31
	v_mul_f32_e32 v39, 0x3d372713, v1
	v_add_f32_e32 v34, 1.0, v34
	v_rcp_f32_e32 v34, v34
	v_mul_f32_e32 v39, v39, v1
	v_fma_f32 v39, v39, v1, v1
	v_mul_f32_e32 v39, 0x3f4c422a, v39
	v_fma_f32 v34, v34, -2.0, 1.0
	v_add_f32_e32 v34, 1.0, v34
	v_mul_f32_e32 v5, v5, v34
	v_mul_f32_e32 v5, v30, v5
	v_and_b32_e32 v30, 0xffff0000, v35
	v_add_f32_e32 v30, v30, v31
	v_mul_f32_e32 v31, 0x3d372713, v7
	v_mul_f32_e32 v31, v31, v7
	v_fma_f32 v31, v31, v7, v7
	v_mul_f32_e32 v31, 0x3f4c422a, v31
	v_add_f32_e32 v31, v31, v31
	v_mul_f32_e32 v31, 0x3fb8aa3b, v31
	v_exp_f32_e32 v31, v31
	v_mul_f32_e32 v7, 0.5, v7
	v_add_f32_e32 v39, v39, v39
	v_mul_f32_e32 v39, 0x3fb8aa3b, v39
	v_add_f32_e32 v31, 1.0, v31
	v_rcp_f32_e32 v31, v31
	v_exp_f32_e32 v39, v39
	v_mul_f32_e32 v1, 0.5, v1
	v_fma_f32 v31, v31, -2.0, 1.0
	v_add_f32_e32 v31, 1.0, v31
	v_mul_f32_e32 v7, v7, v31
	v_mul_f32_e32 v7, v30, v7
	v_lshlrev_b32_e32 v30, 16, v32
	v_lshlrev_b32_e32 v31, 16, v36
	v_add_f32_e32 v30, v31, v30
	v_mul_f32_e32 v31, 0x3d372713, v17
	v_mul_f32_e32 v31, v31, v17
	v_fma_f32 v31, v31, v17, v17
	v_mul_f32_e32 v31, 0x3f4c422a, v31
	v_add_f32_e32 v31, v31, v31
	v_mul_f32_e32 v31, 0x3fb8aa3b, v31
	v_exp_f32_e32 v31, v31
	v_mul_f32_e32 v17, 0.5, v17
	v_add_f32_e32 v39, 1.0, v39
	v_rcp_f32_e32 v39, v39
	v_add_f32_e32 v31, 1.0, v31
	v_rcp_f32_e32 v31, v31
	v_fma_f32 v39, v39, -2.0, 1.0
	v_add_f32_e32 v39, 1.0, v39
	v_fma_f32 v31, v31, -2.0, 1.0
	v_add_f32_e32 v31, 1.0, v31
	v_mul_f32_e32 v17, v17, v31
	v_mul_f32_e32 v17, v30, v17
	v_and_b32_e32 v30, 0xffff0000, v36
	v_and_b32_e32 v31, 0xffff0000, v32
	v_add_f32_e32 v30, v30, v31
	v_mul_f32_e32 v31, 0x3d372713, v19
	v_mul_f32_e32 v31, v31, v19
	v_fma_f32 v31, v31, v19, v19
	v_mul_f32_e32 v31, 0x3f4c422a, v31
	v_add_f32_e32 v31, v31, v31
	v_mul_f32_e32 v31, 0x3fb8aa3b, v31
	v_exp_f32_e32 v31, v31
	v_mul_f32_e32 v19, 0.5, v19
	v_mul_f32_e32 v1, v1, v39
	v_mul_f32_e32 v1, v38, v1
	v_add_f32_e32 v31, 1.0, v31
	v_rcp_f32_e32 v31, v31
	s_nop 0
	v_fma_f32 v31, v31, -2.0, 1.0
	v_add_f32_e32 v31, 1.0, v31
	v_mul_f32_e32 v19, v19, v31
	v_mul_f32_e32 v19, v30, v19
	v_lshlrev_b32_e32 v30, 16, v33
	v_lshlrev_b32_e32 v31, 16, v37
	v_add_f32_e32 v30, v31, v30
	v_mul_f32_e32 v31, 0x3d372713, v21
	v_mul_f32_e32 v31, v31, v21
	v_fma_f32 v31, v31, v21, v21
	v_mul_f32_e32 v31, 0x3f4c422a, v31
	v_add_f32_e32 v31, v31, v31
	v_mul_f32_e32 v31, 0x3fb8aa3b, v31
	v_exp_f32_e32 v31, v31
	v_mul_f32_e32 v21, 0.5, v21
	v_add_f32_e32 v31, 1.0, v31
	v_rcp_f32_e32 v31, v31
	s_nop 0
	v_fma_f32 v31, v31, -2.0, 1.0
	v_add_f32_e32 v31, 1.0, v31
	v_mul_f32_e32 v21, v21, v31
	v_mul_f32_e32 v21, v30, v21
	v_and_b32_e32 v30, 0xffff0000, v37
	v_and_b32_e32 v31, 0xffff0000, v33
	v_add_f32_e32 v30, v30, v31
	v_mul_f32_e32 v31, 0x3d372713, v23
	v_mul_f32_e32 v31, v31, v23
	v_fma_f32 v31, v31, v23, v23
	v_mul_f32_e32 v31, 0x3f4c422a, v31
	v_add_f32_e32 v31, v31, v31
	v_mul_f32_e32 v31, 0x3fb8aa3b, v31
	v_exp_f32_e32 v31, v31
	v_mul_f32_e32 v23, 0.5, v23
	v_add_f32_e32 v31, 1.0, v31
	v_rcp_f32_e32 v31, v31
	s_nop 0
	v_fma_f32 v31, v31, -2.0, 1.0
	v_add_f32_e32 v31, 1.0, v31
	v_mul_f32_e32 v23, v23, v31
	v_mul_f32_e32 v23, v30, v23
	v_cvt_pk_bf16_f32 v30, v1, v3
	v_cvt_pk_bf16_f32 v31, v5, v7
	v_cvt_pk_bf16_f32 v32, v17, v19
	v_cvt_pk_bf16_f32 v33, v21, v23
	global_store_dwordx4 v[24:25], v[30:33], off
; __device__ __forceinline__ f32x8 unpack8(u32x4 w) { f32x8 o; o[0] = bflo(w.x); o[1] = bfhi(w.x); o[2] = bflo(w.y); o[3] = bfhi(w.y); o[4] = bflo(w.z); o[5] = bfhi(w.z); o[6] = bflo(w.w); o[7] = bfhi(w.w); return o; }
; __device__ __forceinline__ float siluf(float x) { return x * sigm(x); }
; __global__ void __launch_bounds__(512, 2) mega_fwd(Args args) {
;     ...
;                                 const f32x8 a = unpack8(*(const u32x4*)(yr + 512 + 8 * lane)), b = unpack8(*(const u32x4*)(yb + 512 + 8 * lane)), z = unpack8(*(const u32x4*)(pr + PC_Z + 8 * lane));
;                                 f32x8 v; float ss = 0.f;
; #pragma unroll
;                                 for (int e = 0; e < 8; ++e) { v[e] = (a[e] + b[e]) * siluf(z[e]); ss += v[e] * v[e]; }
;                                 ss = wave_sum(ss);
	v_mov_b64_e32 v[34:35], v[64:65]
	v_mov_b64_e32 v[36:37], v[66:67]
	v_mov_b64_e32 v[38:39], v[68:69]
	v_mov_b64_e32 v[40:41], v[70:71]
	s_nop 0
	v_mov_b64_e32 v[42:43], v[72:73]
	v_mov_b64_e32 v[44:45], v[74:75]
	v_and_b32_e32 v3, 64, v175
	v_add_u32_e32 v3, 64, v3
	v_xor_b32_e32 v5, 1, v175
	v_cmp_lt_i32_e32 vcc, v5, v3
	v_lshlrev_b32_e32 v30, 16, v34
	v_lshlrev_b32_e32 v32, 16, v38
	v_lshlrev_b32_e32 v46, 16, v42
	v_mul_f32_e32 v1, 0xbfb8aa3b, v46
	v_exp_f32_e32 v1, v1
	v_and_b32_e32 v47, 0xffff0000, v42
	v_and_b32_e32 v33, 0xffff0000, v38
	v_lshlrev_b32_e32 v38, 16, v43
	v_add_f32_e32 v1, 1.0, v1
	v_rcp_f32_e32 v48, v1
	v_mul_f32_e32 v1, 0xbfb8aa3b, v47
	v_exp_f32_e32 v1, v1
	v_and_b32_e32 v31, 0xffff0000, v34
	v_pk_add_f32 v[30:31], v[30:31], v[32:33]
	v_lshlrev_b32_e32 v34, 16, v39
	v_add_f32_e32 v1, 1.0, v1
	v_rcp_f32_e32 v49, v1
	v_mul_f32_e32 v1, 0xbfb8aa3b, v38
	v_exp_f32_e32 v1, v1
	v_cndmask_b32_e32 v5, v175, v5, vcc
	v_pk_mul_f32 v[32:33], v[48:49], v[46:47]
	v_lshlrev_b32_e32 v48, 16, v44
	v_pk_mul_f32 v[30:31], v[30:31], v[32:33]
	v_lshlrev_b32_e32 v32, 16, v35
	v_and_b32_e32 v33, 0xffff0000, v35
	v_and_b32_e32 v35, 0xffff0000, v39
	v_and_b32_e32 v39, 0xffff0000, v43
	v_add_f32_e32 v1, 1.0, v1
	v_rcp_f32_e32 v42, v1
	v_mul_f32_e32 v1, 0xbfb8aa3b, v39
	v_exp_f32_e32 v1, v1
	v_and_b32_e32 v49, 0xffff0000, v44
	v_lshlrev_b32_e32 v44, 16, v45
	v_pk_add_f32 v[32:33], v[32:33], v[34:35]
	v_add_f32_e32 v1, 1.0, v1
	v_rcp_f32_e32 v43, v1
	v_mul_f32_e32 v1, 0xbfb8aa3b, v48
	v_exp_f32_e32 v1, v1
	v_and_b32_e32 v45, 0xffff0000, v45
	v_pk_mul_f32 v[34:35], v[42:43], v[38:39]
	v_lshlrev_b32_e32 v42, 16, v40
	v_add_f32_e32 v1, 1.0, v1
	v_rcp_f32_e32 v50, v1
	v_mul_f32_e32 v1, 0xbfb8aa3b, v49
	v_exp_f32_e32 v1, v1
	v_pk_mul_f32 v[32:33], v[32:33], v[34:35]
	v_lshlrev_b32_e32 v34, 16, v36
	v_and_b32_e32 v35, 0xffff0000, v36
	v_add_f32_e32 v1, 1.0, v1
	v_rcp_f32_e32 v51, v1
	v_mul_f32_e32 v1, 0xbfb8aa3b, v44
	v_exp_f32_e32 v1, v1
	v_and_b32_e32 v43, 0xffff0000, v40
	v_pk_add_f32 v[34:35], v[34:35], v[42:43]
	v_pk_mul_f32 v[42:43], v[50:51], v[48:49]
	v_add_f32_e32 v1, 1.0, v1
	v_rcp_f32_e32 v48, v1
	v_mul_f32_e32 v1, 0xbfb8aa3b, v45
	v_exp_f32_e32 v1, v1
	v_pk_mul_f32 v[46:47], v[30:31], v[30:31]
	v_pk_mul_f32 v[38:39], v[32:33], v[32:33]
	v_pk_mul_f32 v[34:35], v[34:35], v[42:43]
	v_add_f32_e32 v1, 1.0, v1
	v_rcp_f32_e32 v49, v1
	v_add_f32_e32 v1, v46, v47
	v_lshlrev_b32_e32 v36, 16, v37
	v_and_b32_e32 v37, 0xffff0000, v37
	v_lshlrev_b32_e32 v40, 16, v41
	v_and_b32_e32 v41, 0xffff0000, v41
	v_add_f32_e32 v1, v1, v38
	v_pk_mul_f32 v[42:43], v[34:35], v[34:35]
	v_pk_add_f32 v[36:37], v[36:37], v[40:41]
	v_pk_mul_f32 v[40:41], v[48:49], v[44:45]
	v_add_f32_e32 v1, v1, v39
	v_pk_mul_f32 v[36:37], v[36:37], v[40:41]
	v_add_f32_e32 v1, v1, v42
	v_pk_mul_f32 v[40:41], v[36:37], v[36:37]
	v_add_f32_e32 v1, v1, v43
	v_add_f32_e32 v1, v1, v40
	v_add_f32_e32 v1, v1, v41
	v_lshlrev_b32_e32 v5, 2, v5
	ds_bpermute_b32 v7, v5, v1
	s_waitcnt lgkmcnt(0)
	v_add_f32_e32 v1, v1, v7
	v_xor_b32_e32 v7, 2, v175
	v_cmp_lt_i32_e32 vcc, v7, v3
	s_nop 1
	v_cndmask_b32_e32 v7, v175, v7, vcc
	v_lshlrev_b32_e32 v7, 2, v7
	ds_bpermute_b32 v17, v7, v1
	s_waitcnt lgkmcnt(0)
	v_add_f32_e32 v1, v1, v17
	v_xor_b32_e32 v17, 4, v175
	v_cmp_lt_i32_e32 vcc, v17, v3
	s_nop 1
	v_cndmask_b32_e32 v17, v175, v17, vcc
	v_lshlrev_b32_e32 v17, 2, v17
	ds_bpermute_b32 v19, v17, v1
	s_waitcnt lgkmcnt(0)
	v_add_f32_e32 v1, v1, v19
	v_xor_b32_e32 v19, 8, v175
	v_cmp_lt_i32_e32 vcc, v19, v3
	s_nop 1
	v_cndmask_b32_e32 v19, v175, v19, vcc
	v_lshlrev_b32_e32 v19, 2, v19
	ds_bpermute_b32 v21, v19, v1
	s_waitcnt lgkmcnt(0)
	v_add_f32_e32 v1, v1, v21
	v_xor_b32_e32 v21, 16, v175
	v_cmp_lt_i32_e32 vcc, v21, v3
	s_nop 1
	v_cndmask_b32_e32 v21, v175, v21, vcc
	v_lshlrev_b32_e32 v21, 2, v21
	ds_bpermute_b32 v21, v21, v1
	s_waitcnt lgkmcnt(0)
	v_add_f32_e32 v1, v1, v21
	v_xor_b32_e32 v21, 32, v175
	v_cmp_lt_i32_e32 vcc, v21, v3
	s_nop 1
	v_cndmask_b32_e32 v3, v175, v21, vcc
	v_lshlrev_b32_e32 v3, 2, v3
	ds_bpermute_b32 v3, v3, v1
	s_waitcnt lgkmcnt(0)
; __device__ __forceinline__ f32x8 unpack8(u32x4 w) { f32x8 o; o[0] = bflo(w.x); o[1] = bfhi(w.x); o[2] = bflo(w.y); o[3] = bfhi(w.y); o[4] = bflo(w.z); o[5] = bfhi(w.z); o[6] = bflo(w.w); o[7] = bfhi(w.w); return o; }
; __device__ __forceinline__ u32x4 pack8(f32x8 v) { u32x4 w; w.x = pk2(v[0], v[1]); w.y = pk2(v[2], v[3]); w.z = pk2(v[4], v[5]); w.w = pk2(v[6], v[7]); return w; }
; __device__ __forceinline__ float siluf(float x) { return x * sigm(x); }
; __global__ void __launch_bounds__(512, 2) mega_fwd(Args args) {
;     ...
;                                 *(u32x4*)(yr + 512 + 8 * lane) = pack8(v * rs * nw_s);
;                             }
;                             {
;                                 const f32x8 a = unpack8(*(const u32x4*)(yr + 1024 + 8 * lane)), b = unpack8(*(const u32x4*)(yb + 1024 + 8 * lane)), gg = unpack8(*(const u32x4*)(pr + PC_G + 8 * lane));
;                                 f32x8 v = a + b; float s1 = 0.f;
; #pragma unroll
;                                 for (int e = 0; e < 8; ++e) s1 += v[e];
;                                 s1 += __shfl_xor(s1, 1); s1 += __shfl_xor(s1, 2); s1 += __shfl_xor(s1, 4); s1 += __shfl_xor(s1, 8);
;                                 const float mu = s1 * (1.0f / 128.0f); float s2 = 0.f;
; #pragma unroll
;                                 for (int e = 0; e < 8; ++e) { v[e] -= mu; s2 += v[e] * v[e]; }
;                                 s2 += __shfl_xor(s2, 1); s2 += __shfl_xor(s2, 2); s2 += __shfl_xor(s2, 4); s2 += __shfl_xor(s2, 8);
;                                 const float rs = rsqrtf(s2 * (1.0f / 128.0f) + EPSN);
;                                 f32x8 o;
; #pragma unroll
;                                 for (int e = 0; e < 8; ++e) o[e] = v[e] * rs * nw_r[e] * siluf(gg[e]);
;                                 *(u32x4*)(yr + 1024 + 8 * lane) = pack8(o);
;                             }
;                         }
	v_add_f32_e32 v1, v1, v3
	v_fmamk_f32 v1, v1, 0x3b000000, v171
	v_cmp_gt_f32_e32 vcc, s8, v1
	v_mul_f32_e32 v3, 0x4b800000, v1
	s_nop 0
	v_cndmask_b32_e32 v1, v1, v3, vcc
	v_rsq_f32_e32 v1, v1
	s_nop 0
	v_mul_f32_e32 v3, 0x45800000, v1
	v_cndmask_b32_e32 v38, v1, v3, vcc
	v_pk_mul_f32 v[30:31], v[30:31], v[38:39] op_sel_hi:[1,0]
	v_pk_mul_f32 v[32:33], v[32:33], v[38:39] op_sel_hi:[1,0]
	v_pk_mul_f32 v[34:35], v[34:35], v[38:39] op_sel_hi:[1,0]
	v_pk_mul_f32 v[36:37], v[36:37], v[38:39] op_sel_hi:[1,0]
	v_pk_mul_f32 v[32:33], v[14:15], v[32:33]
	v_pk_mul_f32 v[30:31], v[12:13], v[30:31]
	v_pk_mul_f32 v[36:37], v[10:11], v[36:37]
	v_pk_mul_f32 v[34:35], v[8:9], v[34:35]
	v_cvt_pk_bf16_f32 v30, v30, v31
	v_cvt_pk_bf16_f32 v31, v32, v33
	v_add_co_u32_e32 v26, vcc, s1, v26
	v_cvt_pk_bf16_f32 v32, v34, v35
	v_cvt_pk_bf16_f32 v33, v36, v37
	global_store_dwordx4 v[24:25], v[30:33], off offset:1024
	s_nop 1
	v_mov_b64_e32 v[30:31], v[76:77]
	v_mov_b64_e32 v[32:33], v[78:79]
	v_addc_co_u32_e32 v27, vcc, 0, v27, vcc
	s_mul_i32 s1, s58, 0x2400
	s_add_u32 s6, s6, s1
	s_mul_hi_i32 s1, s58, 0x2400
	s_addc_u32 s7, s7, s1
	s_mul_i32 s1, s58, 0xc00
	s_add_u32 s4, s4, s1
	s_mul_hi_i32 s1, s58, 0xc00
	s_addc_u32 s5, s5, s1
	s_cmp_gt_i32 s0, 0x9fff
	v_lshlrev_b32_e32 v34, 16, v30
	v_and_b32_e32 v35, 0xffff0000, v30
	v_lshlrev_b32_e32 v36, 16, v31
	v_and_b32_e32 v37, 0xffff0000, v31
	v_mov_b64_e32 v[28:29], v[80:81]
	v_mov_b64_e32 v[30:31], v[82:83]
	v_lshlrev_b32_e32 v38, 16, v32
	v_and_b32_e32 v39, 0xffff0000, v32
	v_lshlrev_b32_e32 v32, 16, v33
	v_and_b32_e32 v33, 0xffff0000, v33
	v_lshlrev_b32_e32 v40, 16, v28
	v_and_b32_e32 v41, 0xffff0000, v28
	v_lshlrev_b32_e32 v42, 16, v29
	v_and_b32_e32 v43, 0xffff0000, v29
	v_mov_b64_e32 v[26:27], v[84:85]
	v_mov_b64_e32 v[28:29], v[86:87]
	v_pk_add_f32 v[34:35], v[34:35], v[40:41]
	v_pk_add_f32 v[36:37], v[36:37], v[42:43]
	v_add_f32_e32 v1, 0, v34
	v_add_f32_e32 v1, v35, v1
	v_lshlrev_b32_e32 v44, 16, v30
	v_and_b32_e32 v45, 0xffff0000, v30
	v_lshlrev_b32_e32 v30, 16, v31
	v_and_b32_e32 v31, 0xffff0000, v31
	v_add_f32_e32 v1, v36, v1
	v_pk_add_f32 v[30:31], v[32:33], v[30:31]
	v_pk_add_f32 v[32:33], v[38:39], v[44:45]
	v_add_f32_e32 v1, v37, v1
	v_add_f32_e32 v1, v32, v1
	v_add_f32_e32 v1, v33, v1
	v_add_f32_e32 v1, v30, v1
	v_add_f32_e32 v1, v31, v1
	ds_bpermute_b32 v3, v5, v1
	s_waitcnt lgkmcnt(0)
	v_add_f32_e32 v1, v1, v3
	ds_bpermute_b32 v3, v7, v1
	s_waitcnt lgkmcnt(0)
	v_add_f32_e32 v1, v1, v3
	ds_bpermute_b32 v3, v17, v1
	s_waitcnt lgkmcnt(0)
	v_add_f32_e32 v1, v1, v3
	ds_bpermute_b32 v3, v19, v1
	s_waitcnt lgkmcnt(0)
	v_add_f32_e32 v1, v1, v3
	v_fmac_f32_e32 v35, 0xbc000000, v1
	v_fmamk_f32 v3, v1, 0xbc000000, v34
	v_lshlrev_b32_e32 v47, 16, v26
	v_and_b32_e32 v49, 0xffff0000, v26
	v_lshlrev_b32_e32 v51, 16, v27
	v_and_b32_e32 v27, 0xffff0000, v27
	v_mul_f32_e32 v26, 0x3c000000, v1
	v_mul_f32_e32 v1, v35, v35
	v_pk_add_f32 v[36:37], v[36:37], v[26:27] op_sel_hi:[1,0] neg_lo:[0,1] neg_hi:[0,1]
	v_fmac_f32_e32 v1, v3, v3
	v_pk_mul_f32 v[38:39], v[36:37], v[36:37]
	v_pk_add_f32 v[32:33], v[32:33], v[26:27] op_sel_hi:[1,0] neg_lo:[0,1] neg_hi:[0,1]
	v_add_f32_e32 v1, v1, v38
	v_add_f32_e32 v1, v1, v39
	v_pk_mul_f32 v[38:39], v[32:33], v[32:33]
	v_pk_add_f32 v[30:31], v[30:31], v[26:27] op_sel_hi:[1,0] neg_lo:[0,1] neg_hi:[0,1]
	v_add_f32_e32 v1, v1, v38
	v_add_f32_e32 v1, v1, v39
	v_pk_mul_f32 v[38:39], v[30:31], v[30:31]
	v_and_b32_e32 v55, 0xffff0000, v28
	v_add_f32_e32 v1, v1, v38
	v_add_f32_e32 v1, v1, v39
	ds_bpermute_b32 v5, v5, v1
	v_lshlrev_b32_e32 v53, 16, v28
	v_lshlrev_b32_e32 v57, 16, v29
	v_and_b32_e32 v29, 0xffff0000, v29
	s_waitcnt lgkmcnt(0)
	v_add_f32_e32 v1, v1, v5
	ds_bpermute_b32 v5, v7, v1
	s_waitcnt lgkmcnt(0)
	v_add_f32_e32 v1, v1, v5
	ds_bpermute_b32 v5, v17, v1
	s_waitcnt lgkmcnt(0)
	v_add_f32_e32 v1, v1, v5
	ds_bpermute_b32 v5, v19, v1
	s_waitcnt lgkmcnt(0)
	v_add_f32_e32 v1, v1, v5
	v_fmamk_f32 v1, v1, 0x3c000000, v171
	v_cmp_gt_f32_e32 vcc, s8, v1
	v_mul_f32_e32 v5, 0x4b800000, v1
	s_nop 0
	v_cndmask_b32_e32 v1, v1, v5, vcc
	v_rsq_f32_e32 v1, v1
	s_nop 0
	v_mul_f32_e32 v5, 0x45800000, v1
	v_cndmask_b32_e32 v17, v1, v5, vcc
	v_mul_f32_e32 v1, 0xbfb8aa3b, v47
	v_exp_f32_e32 v1, v1
	v_mul_f32_e32 v46, v17, v3
	v_mul_f32_e32 v3, 0xbfb8aa3b, v55
	v_exp_f32_e32 v3, v3
	v_add_f32_e32 v1, 1.0, v1
	v_rcp_f32_e32 v5, v1
	v_mul_f32_e32 v1, 0xbfb8aa3b, v49
	v_exp_f32_e32 v1, v1
	v_add_f32_e32 v3, 1.0, v3
	v_rcp_f32_e32 v19, v3
	v_mul_f32_e32 v3, 0xbfb8aa3b, v57
	v_add_f32_e32 v1, 1.0, v1
	v_rcp_f32_e32 v23, v1
	v_mul_f32_e32 v1, 0xbfb8aa3b, v51
	v_exp_f32_e32 v1, v1
	v_mul_f32_e32 v48, v17, v35
	v_mul_f32_e32 v50, v17, v36
	v_mul_f32_e32 v26, v17, v37
	v_add_f32_e32 v1, 1.0, v1
	v_rcp_f32_e32 v7, v1
	v_mul_f32_e32 v1, 0xbfb8aa3b, v27
	v_exp_f32_e32 v1, v1
	v_mul_f32_e32 v52, v17, v32
	v_mul_f32_e32 v54, v17, v33
	v_mul_f32_e32 v56, v17, v30
	v_add_f32_e32 v1, 1.0, v1
	v_rcp_f32_e32 v21, v1
	v_mul_f32_e32 v1, 0xbfb8aa3b, v53
	v_exp_f32_e32 v1, v1
	v_exp_f32_e32 v3, v3
	v_mul_f32_e32 v28, v17, v31
	v_mul_f32_e32 v17, 0xbfb8aa3b, v29
	v_exp_f32_e32 v17, v17
	v_add_f32_e32 v1, 1.0, v1
	v_rcp_f32_e32 v1, v1
	v_add_f32_e32 v3, 1.0, v3
	v_rcp_f32_e32 v3, v3
	v_add_f32_e32 v17, 1.0, v17
	v_pk_mul_f32 v[26:27], v[20:21], v[26:27]
	v_rcp_f32_e32 v17, v17
	v_mul_f32_e32 v21, v26, v27
	v_pk_mul_f32 v[26:27], v[0:1], v[52:53]
	v_pk_mul_f32 v[34:35], v[22:23], v[48:49]
	v_mul_f32_e32 v1, v26, v27
	v_pk_mul_f32 v[26:27], v[18:19], v[54:55]
	v_pk_mul_f32 v[38:39], v[4:5], v[46:47]
	v_mul_f32_e32 v19, v26, v27
	v_pk_mul_f32 v[26:27], v[2:3], v[56:57]
	v_mul_f32_e32 v23, v34, v35
	v_pk_mul_f32 v[34:35], v[6:7], v[50:51]
	v_mul_f32_e32 v3, v26, v27
	v_pk_mul_f32 v[26:27], v[16:17], v[28:29]
	v_mul_f32_e32 v5, v38, v39
	v_mul_f32_e32 v7, v34, v35
	v_mul_f32_e32 v17, v26, v27
	v_cvt_pk_bf16_f32 v26, v5, v23
	v_cvt_pk_bf16_f32 v27, v7, v21
	v_cvt_pk_bf16_f32 v28, v1, v19
	v_cvt_pk_bf16_f32 v29, v3, v17
	global_store_dwordx4 v[24:25], v[26:29], off offset:2048
	s_cbranch_scc0 .LBB0_726
